# v60 + RWKV staging: wave 0 (critical solve wave) keeps plain 2-byte writes (no permlane/perm VALU), waves 1-7 packed dwords
# speedup vs baseline: 1.0078x; 1.0075x over previous
; #define LAS __attribute__((address_space(3)))
; __device__ __forceinline__ void rwkv_chunk_item(const P& p, const Ctx& c, int seg, int w, bool save) {
;     ...
;     auto lstore = [&](int pb, int tidv) { const int t = tidv >> 5, j0 = (tidv & 31) * 2;
;         LAS bf16_t* EA = (LAS bf16_t*)(OB + pb * OPB + O_EA); LAS bf16_t* EB = (LAS bf16_t*)(OB + pb * OPB + O_EB); LAS bf16_t* EBT = (LAS bf16_t*)(OB + pb * OPB + O_EBT);
;         LAS bf16_t* UV = (LAS bf16_t*)(OB + pb * OPB + O_UV); LAS float* GT = (LAS float*)(OB + pb * OPB + O_GT);
;         *(LAS unsigned*)(EA + t * 72 + j0) = ga; *(LAS unsigned*)(EA + (16 + t) * 72 + j0) = gr;
;         *(LAS unsigned*)(EB + t * 72 + j0) = gb; *(LAS unsigned*)(EB + (16 + t) * 72 + j0) = gk;
;         EBT[j0 * 40 + t] = (bf16_t)(gb & 0xFFFFu); EBT[(j0 + 1) * 40 + t] = (bf16_t)(gb >> 16); EBT[j0 * 40 + 16 + t] = (bf16_t)(gk & 0xFFFFu); EBT[(j0 + 1) * 40 + 16 + t] = (bf16_t)(gk >> 16);
;         UV[j0 * 40 + 16 + t] = (bf16_t)(gv & 0xFFFFu); UV[(j0 + 1) * 40 + 16 + t] = (bf16_t)(gv >> 16); UV[j0 * 40 + t] = 0; UV[(j0 + 1) * 40 + t] = 0;
;         if (tidv < 64) GT[tidv] = gg; };
.Lrw_early_skip:
	s_cmp_eq_u32 s86, 31
	s_cselect_b64 s[4:5], -1, 0
	s_and_b64 vcc, exec, s[4:5]
	v_ashrrev_i32_e32 v46, 5, v44
	v_lshlrev_b32_e32 v45, 1, v44
	v_cmp_gt_i32_e64 s[2:3], 64, v44
	s_cbranch_vccnz .LBB0_931
	s_xor_b32 s78, s87, 1
	v_and_b32_e32 v47, 62, v45
	s_mulk_i32 s78, 0x5c00
	s_add_i32 s89, s78, 0
	v_mul_lo_u32 v48, v46, s63
	v_lshlrev_b32_e32 v49, 1, v47
	v_mad_u32_u24 v47, v47, 40, v46
	v_add3_u32 v48, s89, v48, v49
	v_lshl_add_u32 v47, v47, 1, s89
	s_waitcnt vmcnt(0)
	ds_write2st64_b32 v48, v71, v76 offset1:9
	ds_write2st64_b32 v48, v74, v75 offset0:18 offset1:27
	s_andn2_b64 vcc, exec, s[70:71]
	s_cbranch_vccnz .Lrw_st_b32
	ds_write_b16 v47, v74 offset:9216
	ds_write_b16_d16_hi v47, v74 offset:9296
	ds_write_b16 v47, v75 offset:9248
	ds_write_b16_d16_hi v47, v75 offset:9328
	ds_write_b16 v47, v79 offset:14368
	ds_write_b16_d16_hi v47, v79 offset:14448
	ds_write_b16 v47, v5 offset:14336
	ds_write_b16 v47, v5 offset:14416
	s_branch .Lrw_st_done
.Lrw_st_b32:
	v_bfe_u32 v104, v44, 5, 1
	v_cmp_ne_u32_e32 vcc, 0, v104
	v_mov_b32_e32 v105, 0x5040100
	v_mov_b32_e32 v106, 0x7060302
	v_mul_u32_u24_e32 v104, 0x4e, v104
	v_cndmask_b32_e32 v105, v105, v106, vcc
	v_add_u32_e32 v104, v47, v104
	v_mov_b32_e32 v106, v74
	v_mov_b32_e32 v107, v74
	s_nop 1
	v_permlane32_swap_b32_e32 v106, v107
	v_perm_b32 v108, v107, v106, v105
	ds_write_b32 v104, v108 offset:9216
	v_mov_b32_e32 v106, v75
	v_mov_b32_e32 v107, v75
	s_nop 1
	v_permlane32_swap_b32_e32 v106, v107
	v_perm_b32 v108, v107, v106, v105
	ds_write_b32 v104, v108 offset:9248
	v_mov_b32_e32 v106, v79
	v_mov_b32_e32 v107, v79
	s_nop 1
	v_permlane32_swap_b32_e32 v106, v107
	v_perm_b32 v108, v107, v106, v105
	ds_write_b32 v104, v108 offset:14368
	ds_write_b32 v104, v5 offset:14336
.Lrw_st_done:
	s_and_saveexec_b64 s[78:79], s[2:3]
	v_lshl_add_u32 v47, v44, 2, s89
	ds_write_b32 v47, v27 offset:23296
	s_or_b64 exec, exec, s[78:79]
	s_cmp_gt_u32 s86, 29
	s_cbranch_scc0 .LBB0_932
